# P2: DUt and the two [132:133] parameter loads hoisted to the item top (regs freed by folding LDS address constants into DS offsets and rebuilding one-hot constants at use); no dependent global round t
# speedup vs baseline: 1.0111x; 1.0066x over previous
; __device__ void rwkv_prep_item(const Params& p, char* lds_, int item, PrepRaw& raw, int next_item) {
;     ...
; #pragma unroll
;     for (int e = 0; e < 8; ++e) th[e] = 1.f - 2.f * __builtin_amdgcn_rcpf(1.f + fexp(2.f * wd[e]));
;     w.x = pk2(th[0], th[1]); w.y = pk2(th[2], th[3]); w.z = pk2(th[4], th[5]); w.w = pk2(th[6], th[7]);
;     *(u32x4*)(TW + t * LD + cg8) = w;
;     w.x = pk2(ad[0], ad[1]); w.y = pk2(ad[2], ad[3]); w.z = pk2(ad[4], ad[5]); w.w = pk2(ad[6], ad[7]);
;     *(u32x4*)(AD + t * LD + cg8) = w;
;     *(u32x4*)(DUs + t * LD + cg8) = *(const u32x4*)(p.DUt + (size_t)(hd * 64 + t) * 64 + cg8);
;     *(u32x4*)(IUs + t * LD + cg8) = *(const u32x4*)(p.IUt + (size_t)(hd * 64 + t) * 64 + cg8);
;     ...
; #pragma unroll
;     for (int jj = 0; jj < 2; ++jj) {
;       const int j0 = (jt0 + jj) * 16 + 4 * mg;
;       f32x4 o; float x1[4], x2[4], x3[4];
; #pragma unroll
;       for (int e = 0; e < 4; ++e) {
;         const int j = j0 + e;
;         o[e] = (j < mi) ? lab[jj][e] : 0.f;
;         x1[e] = (j < mi) ? lak[jj][e] : 0.f;
;         x2[e] = (j <= mi) ? mrb[jj][e] : 0.f;
;         x3[e] = (j <= mi) ? mrk[jj][e] : 0.f;
;       }
;       *(f32x4*)(Tf + mi * 68 + j0) = o;
;       u32x2 w;
;       w.x = pk2(x1[0], x1[1]); w.y = pk2(x1[2], x1[3]); *(u32x2*)(LAK + mi * LD + j0) = w;
;       w.x = pk2(x2[0], x2[1]); w.y = pk2(x2[2], x2[3]); *(u32x2*)(MRB + mi * LD + j0) = w;
;       w.x = pk2(x3[0], x3[1]); w.y = pk2(x3[2], x3[3]); *(u32x2*)(MRK + mi * LD + j0) = w;
;     }
;   }
;   __syncthreads();
;   {
;     float* Ms = Za;
;     const int r16 = lane & 15, g4 = lane >> 4;
;     if (wave == 0) {
;       const float* Lk = Tf + (16 * g4) * 68 + 16 * g4;
;       float xv[16];
; #pragma unroll
;       for (int i = 0; i < 16; ++i) {
;         float sacc = (i == r16) ? 1.f : 0.f;
; #pragma unroll
;         for (int q = 0; q < (i + 3) / 4; ++q) {
;           const f32x4 Lv = *(const f32x4*)(Lk + i * 68 + 4 * q);
; #pragma unroll
;           for (int e = 0; e < 4; ++e)
;             if (4 * q + e < i) sacc += Lv[e] * xv[4 * q + e];
;         }
;         xv[i] = sacc;
;       }
;       float* Dk = Tf + (16 * g4) * 68 + 16 * g4 + r16;
; #pragma unroll
;       for (int i = 0; i < 16; ++i) Dk[i * 68] = xv[i];
;     }
;     __syncthreads();
;     if (wave < 2) {
;       const int R = 32 * wave + 16, C = 32 * wave;
;       f32x4 m = {0.f, 0.f, 0.f, 0.f};
; #pragma unroll
.LBB0_273:
.LBB0_274:
	v_bfe_u32 v115, v223, 4, 2
	s_andn2_b64 vcc, exec, s[4:5]
	v_lshrrev_b32_e32 v158, 6, v223
	v_and_b32_e32 v174, 15, v223
	v_lshrrev_b32_e32 v175, 1, v223
	v_lshlrev_b32_e32 v114, 2, v115
	s_cbranch_vccnz .LBB0_330
	v_lshlrev_b32_e32 v28, 5, v158
	v_and_or_b32 v30, v28, 32, v174
	v_and_b32_e32 v29, 24, v175
	v_mul_u32_u24_e32 v24, 0x48, v30
	s_add_i32 s5, 0, 0x18d00
	v_and_b32_e32 v26, 0x70, v240
	v_lshlrev_b32_e32 v35, 1, v24
	v_or_b32_e32 v36, 32, v29
	v_or_b32_e32 v27, v26, v174
	v_lshlrev_b32_e32 v31, 1, v29
	v_lshlrev_b32_e32 v37, 1, v36
	v_add_u32_e32 v24, s5, v35
	v_add_u32_e32 v167, v24, v31
	v_add_u32_e32 v168, v24, v37
	v_mul_u32_u24_e32 v24, 0x44, v27
	v_bfe_u32 v25, v223, 6, 1
	v_lshlrev_b32_e32 v24, 2, v24
	s_add_i32 s15, 0, 0x1b100
	s_add_i32 s74, 0, 0x1f600
	v_add_u32_e32 v39, s15, v24
	v_add_u32_e32 v40, s74, v24
	v_lshlrev_b32_e32 v41, 7, v25
	v_and_b32_e32 v24, 48, v223
	v_and_b32_e32 v116, 56, v219
	v_add3_u32 v170, v39, v24, v41
	v_mul_u32_u24_e32 v39, 0x44, v240
	v_add_lshl_u32 v39, v39, v116, 2
	v_add_u32_e32 v172, s15, v39
	v_add_u32_e32 v173, s74, v39
	v_add_u32_e32 v39, 16, v39
	v_add_u32_e32 v176, s15, v39
	v_add_u32_e32 v177, s74, v39
	v_mbcnt_hi_u32_b32 v39, -1, v241
	v_add3_u32 v171, v40, v24, v41
	v_and_b32_e32 v41, 64, v39
	v_xor_b32_e32 v40, 1, v39
	v_add_u32_e32 v41, 64, v41
	v_cmp_lt_i32_e32 vcc, v40, v41
	v_mul_u32_u24_e32 v22, 0x48, v240
	v_mov_b32_e32 v242, v241
	v_cndmask_b32_e32 v40, v39, v40, vcc
	v_lshlrev_b32_e32 v178, 2, v40
	v_xor_b32_e32 v40, 2, v39
	v_cmp_lt_i32_e32 vcc, v40, v41
	s_add_i32 s14, 0, 0x12100
	v_lshlrev_b32_e32 v23, 1, v22
	v_cndmask_b32_e32 v40, v39, v40, vcc
	v_lshlrev_b32_e32 v179, 2, v40
	v_xor_b32_e32 v40, 4, v39
	v_cmp_lt_i32_e32 vcc, v40, v41
	v_lshlrev_b32_e32 v22, 1, v116
	s_add_i32 s4, 0, 0x14500
	v_cndmask_b32_e32 v39, v39, v40, vcc
	v_cmp_eq_u32_e32 vcc, 0, v174
	s_add_i32 s10, 0, 0x16900
	v_mul_u32_u24_e32 v47, 0x110, v24
	v_cndmask_b32_e64 v190, 0, 1.0, vcc
	v_cmp_eq_u32_e32 vcc, 1, v174
	v_lshlrev_b32_e32 v48, 2, v24
	v_add3_u32 v117, s14, v23, v22
	v_cndmask_b32_e64 v191, 0, 1.0, vcc
	v_cmp_eq_u32_e32 vcc, 2, v174
	v_cndmask_b32_e64 v253, 0, 1.0, vcc
	v_cmp_eq_u32_e32 vcc, 3, v174
	v_mul_u32_u24_e32 v32, 0x48, v27
	v_cndmask_b32_e64 v254, 0, 1.0, vcc
	v_cmp_eq_u32_e32 vcc, 4, v174
	v_add3_u32 v184, 0, v23, v22
	v_bitop3_b32 v23, v219, v240, 56 bitop3:0x6c
	v_cndmask_b32_e64 v255, 0, 1.0, vcc
	v_cmp_eq_u32_e32 vcc, 5, v174
	v_add3_u32 v189, s15, v47, v48
	v_lshlrev_b32_e32 v47, 2, v174
	v_cndmask_b32_e64 v241, 0, 1.0, vcc
	v_cmp_eq_u32_e32 vcc, 6, v174
	v_or_b32_e32 v48, 16, v28
	v_lshlrev_b32_e32 v120, 6, v25
	v_cndmask_b32_e64 v196, 0, 1.0, vcc
	v_cmp_eq_u32_e32 vcc, 7, v174
	v_lshlrev_b32_e32 v32, 1, v32
	s_movk_i32 s16, 0x110
	v_cndmask_b32_e64 v197, 0, 1.0, vcc
	v_cmp_eq_u32_e32 vcc, 8, v174
	v_mul_u32_u24_e32 v43, 0x90, v116
	v_lshlrev_b32_e32 v23, 1, v23
	v_cndmask_b32_e64 v198, 0, 1.0, vcc
	v_cmp_eq_u32_e32 vcc, 9, v174
	v_or_b32_e32 v49, v48, v174
	v_add3_u32 v211, s15, v120, v47
	v_or_b32_e32 v26, v114, v26
	v_add3_u32 v185, 0, v43, v23
	v_add_u32_e32 v23, 0, v32
	v_cndmask_b32_e64 v199, 0, 1.0, vcc
	v_cmp_eq_u32_e32 vcc, 10, v174
	v_mul_u32_u24_e32 v49, 0x110, v49
	v_lshl_add_u32 v50, v158, 7, s15
	v_or_b32_e32 v28, v28, v115
	v_mul_u32_u24_e32 v52, 0x84, v26
	v_mad_u32_u24 v212, v26, s16, v211
	v_bitop3_b32 v26, v27, v29, 56 bitop3:0x6c
	v_cndmask_b32_e64 v200, 0, 1.0, vcc
	v_cmp_eq_u32_e32 vcc, 11, v174
	v_add3_u32 v207, v50, v49, v114
	v_add_u32_e32 v49, v50, v47
	v_mul_u32_u24_e32 v50, 0x110, v28
	v_mul_u32_u24_e32 v28, 0x440, v158
	v_lshl_add_u32 v213, v26, 1, v23
	v_add_u32_e32 v26, s14, v35
	v_lshlrev_b32_e32 v180, 2, v39
	v_mul_u32_u24_e32 v39, 0x110, v240
	v_lshlrev_b32_e32 v40, 2, v116
	v_add_u32_e32 v43, 0, v35
	v_cndmask_b32_e64 v201, 0, 1.0, vcc
	v_cmp_eq_u32_e32 vcc, 12, v174
	v_add3_u32 v208, s74, v28, v47
	v_or_b32_e32 v28, v48, v114
	v_add_u32_e32 v214, v26, v31
	v_add_u32_e32 v216, v26, v37
	v_bitop3_b32 v26, v30, v29, 40 bitop3:0x6c
	v_add3_u32 v181, s15, v39, v40
	v_lshlrev_b32_e32 v39, 2, v222
	v_cndmask_b32_e64 v202, 0, 1.0, vcc
	v_cmp_eq_u32_e32 vcc, 13, v174
	v_mul_u32_u24_e32 v48, 0x110, v28
	v_bitop3_b32 v28, v27, v36, 56 bitop3:0x6c
	v_lshl_add_u32 v222, v26, 1, v43
	v_or_b32_e32 v26, 16, v30
	v_cndmask_b32_e64 v203, 0, 1.0, vcc
	v_cmp_eq_u32_e32 vcc, 14, v174
	v_lshl_add_u32 v215, v28, 1, v23
	v_mul_u32_u24_e32 v28, 0x48, v26
	s_add_i32 s44, 0, 0x1f500
	v_lshl_or_b32 v46, v25, 1, 1
	v_cndmask_b32_e64 v204, 0, 1.0, vcc
	v_cmp_eq_u32_e32 vcc, 15, v174
	v_lshl_add_u32 v28, v28, 1, 0
	v_bitop3_b32 v29, v26, v29, 56 bitop3:0x6c
	v_bitop3_b32 v26, v26, v36, 56 bitop3:0x6c
	v_lshl_or_b32 v25, v25, 5, v114
	s_cmp_lg_u32 0, -1
	v_cndmask_b32_e64 v205, 0, 1.0, vcc
	v_lshl_add_u32 v224, v29, 1, v28
	v_lshl_add_u32 v226, v26, 1, v28
	v_or_b32_e32 v28, 1, v25
	v_cmp_eq_u32_e32 vcc, v25, v27
	v_add_u32_e32 v41, s15, v39
	s_cselect_b64 s[76:77], -1, 0
	v_mov_b32_e32 v44, s15
	s_add_i32 s15, 0, 0x1fe80
	v_bitop3_b32 v29, v30, v36, 40 bitop3:0x6c
	v_cmp_lt_u32_e64 s[18:19], v28, v27
	v_cndmask_b32_e64 v122, 0, 1.0, vcc
	v_cmp_eq_u32_e32 vcc, v28, v27
	v_or_b32_e32 v28, 3, v25
	v_add_u32_e32 v33, s14, v32
	v_mad_u32_u24 v44, v27, s16, v44
	v_add_u32_e32 v206, v189, v47
	v_add3_u32 v47, s15, v120, v47
	v_add3_u32 v217, s14, v37, v35
	v_lshl_add_u32 v225, v29, 1, v43
	v_cmp_lt_u32_e64 s[14:15], v25, v27
	v_cmp_gt_u32_e64 s[16:17], v25, v27
	v_lshlrev_b32_e32 v29, 2, v25
	v_lshlrev_b32_e32 v26, 1, v25
	v_cndmask_b32_e64 v123, 0, 1.0, vcc
	v_or_b32_e32 v25, 2, v25
	v_cmp_eq_u32_e32 vcc, v28, v27
	s_load_dwordx2 s[78:79], s[0:1], 0xb8
	s_load_dwordx4 s[60:63], s[0:1], 0x18
	s_load_dwordx2 s[80:81], s[0:1], 0x30
	s_load_dwordx4 s[64:67], s[0:1], 0x40
	s_load_dwordx2 s[82:83], s[0:1], 0x50
	s_load_dwordx2 s[84:85], s[0:1], 0xf0
	v_cmp_lt_u32_e64 s[20:21], v25, v27
	v_cmp_gt_u32_e64 s[22:23], v25, v27
	v_cndmask_b32_e64 v125, 0, 1.0, vcc
	v_cmp_eq_u32_e32 vcc, v25, v27
	v_lshl_or_b32 v25, v46, 4, v114
	s_load_dwordx8 s[52:59], s[0:1], 0xd0
	v_mov_b32_e32 v119, 0
	v_lshlrev_b32_e32 v30, 2, v25
	v_or_b32_e32 v118, 0x1800, v40
	v_add_u32_e32 v183, s44, v40
	v_lshl_add_u32 v228, v27, 2, s44
	v_add_u32_e32 v229, v44, v29
	v_cmp_lt_u32_e64 s[24:25], v28, v27
	v_cmp_gt_u32_e64 s[26:27], v28, v27
	v_cndmask_b32_e64 v124, 0, 1.0, vcc
	v_add_u32_e32 v234, s44, v29
	v_or_b32_e32 v29, 1, v25
	v_lshlrev_b32_e32 v28, 1, v25
	v_cmp_eq_u32_e32 vcc, v25, v27
	v_add_u32_e32 v243, s44, v30
	s_waitcnt lgkmcnt(0)
; __device__ __forceinline__ unsigned pk2(float lo, float hi) { f32x2_t v = {lo, hi}; bf16x2_t b = __builtin_convertvector(v, bf16x2_t); return __builtin_bit_cast(unsigned, b); }
; __device__ __forceinline__ float bflo(unsigned v) { return __uint_as_float(v << 16); }
; __device__ void rwkv_prep_item(const Params& p, char* lds_, int item, PrepRaw& raw, int next_item) {
;     ...
;     {
;       const float* tr = Tf + t * 68 + cg8;
;       u32x4 w; w.x = pk2(tr[0], tr[1]); w.y = pk2(tr[2], tr[3]); w.z = pk2(tr[4], tr[5]); w.w = pk2(tr[6], tr[7]);
;       *(u32x4*)(TB + t * LD + cg8) = w;
;     }
;   }
;   __syncthreads();
;   {
;     f32x4 a1[2], a2[2]; zero2(a1); zero2(a2);
;     mm_nt<true, false>(VT, LAK, a1, wave, lane);
;     mm_nt<true, false>(AT, TB, a2, wave, lane);
; #pragma unroll
;     for (int jj = 0; jj < 2; ++jj) {
;       const int j0 = (jt0 + jj) * 16 + 4 * mg;
;       u32x2 w;
;       w.x = pk2(a1[jj][0], a1[jj][1]); w.y = pk2(a1[jj][2], a1[jj][3]); *(u32x2*)(X1T + mi * LD + j0) = w;
;       w.x = pk2(a2[jj][0], a2[jj][1]); w.y = pk2(a2[jj][2], a2[jj][3]); *(u32x2*)(WT + mi * LD + j0) = w;
;     }
;     ...
; #pragma unroll
;     for (int jj = 0; jj < 2; ++jj) {
;       const int jt = jt0 + jj, j0 = jt * 16 + 4 * mg;
;       float pv[4];
; #pragma unroll
;       for (int e = 0; e < 4; ++e) pv[e] = gci * (pp[jj][e] + ((j0 + e) == mi ? 1.f : 0.f));
;       u32x2 w; w.x = pk2(pv[0], pv[1]); w.y = pk2(pv[2], pv[3]);
;       *(u32x2*)(p.Pm + (size_t)item * 4096 + mi * 64 + (jt >> 1) * 32 + 8 * mg + 4 * (jt & 1)) = w;
;       const f32x4 gj = *(const f32x4*)(gC + j0);
;       { u32x2 qw; qw.x = pk2(qt[jj][0] * gj[0], qt[jj][1] * gj[1]); qw.y = pk2(qt[jj][2] * gj[2], qt[jj][3] * gj[3]);
;         *(u32x2*)(p.QT + (size_t)item * 4096 + mi * 64 + j0) = qw; }
;       const u32x2 rw = *(const u32x2*)(Rt + mi * LD + j0);
;       w.x = pk2(ry[jj][0] + bflo(rw.x), ry[jj][1] + bfhi(rw.x)); w.y = pk2(ry[jj][2] + bflo(rw.y), ry[jj][3] + bfhi(rw.y));
;       *(u32x2*)(p.Ry + (size_t)item * 4096 + mi * 64 + j0) = w;
;     ...
;       { const u32x2 dw = *(const u32x2*)(DBG_DUMP_SRC + mi * LD + j0); y0[jj][0] = bflo(dw.x); y0[jj][1] = bfhi(dw.x); y0[jj][2] = bflo(dw.y); y0[jj][3] = bfhi(dw.y); }
;     ...
;       { u32x2 yw; yw.x = pk2(y0[jj][0], y0[jj][1]); yw.y = pk2(y0[jj][2], y0[jj][3]);
;         *(u32x2*)(p.Y0 + (size_t)item * 4096 + mi * 64 + j0) = yw; }
	v_lshl_add_u64 v[130:131], s[60:61], 0, v[118:119]
	v_or_b32_e32 v118, 0x1900, v40
	s_load_dwordx4 s[44:47], s[0:1], 0x128
	v_add_u32_e32 v38, s4, v32
	v_add_u32_e32 v187, v23, v31
	v_lshl_add_u32 v221, v115, 3, v23
	v_add_u32_e32 v233, v23, v26
	v_add_u32_e32 v239, v23, v28
	v_cndmask_b32_e64 v126, 0, 1.0, vcc
	v_cmp_eq_u32_e32 vcc, v29, v27
	v_or_b32_e32 v23, 3, v25
	v_lshl_add_u64 v[132:133], s[60:61], 0, v[118:119]
	v_lshlrev_b32_e32 v118, 7, v240
	v_add_u32_e32 v162, v33, v31
	v_add_u32_e32 v34, s10, v31
	v_add_u32_e32 v166, v38, v31
	v_add_u32_e32 v188, v43, v31
	v_add_u32_e32 v235, v44, v30
	v_cndmask_b32_e64 v127, 0, 1.0, vcc
	v_cmp_lt_u32_e64 s[40:41], v23, v27
	v_cmp_gt_u32_e64 s[42:43], v23, v27
	v_cmp_eq_u32_e32 vcc, v23, v27
	v_mov_b32_e32 v23, v119
	v_lshl_add_u64 v[30:31], s[84:85], 0, v[118:119]
	v_lshlrev_b32_e32 v118, 7, v27
	v_cmp_lt_u32_e64 s[28:29], v25, v27
	v_cmp_gt_u32_e64 s[30:31], v25, v27
	v_or_b32_e32 v25, 2, v25
	v_lshl_add_u64 v[134:135], s[52:53], 0, v[22:23]
	v_lshl_add_u64 v[136:137], s[54:55], 0, v[22:23]
	v_lshl_add_u64 v[138:139], v[30:31], 0, v[22:23]
	v_lshl_add_u64 v[22:23], s[56:57], 0, v[118:119]
	v_mov_b32_e32 v121, v119
	v_cmp_lt_u32_e64 s[36:37], v25, v27
	v_cmp_gt_u32_e64 s[38:39], v25, v27
	v_cndmask_b32_e64 v129, 0, 1.0, vcc
	v_cmp_eq_u32_e32 vcc, v25, v27
	v_lshl_add_u64 v[22:23], v[22:23], 0, v[120:121]
	v_mov_b32_e32 v25, v119
	v_cmp_lt_u32_e64 s[34:35], v29, v27
	v_lshl_add_u64 v[140:141], v[22:23], 0, v[24:25]
	s_waitcnt lgkmcnt(0)
	v_lshl_add_u64 v[22:23], s[44:45], 0, v[118:119]
	v_mov_b32_e32 v27, v119
	v_mov_b32_e32 v29, v119
	v_add_u32_e32 v163, v34, v35
	v_add3_u32 v164, s10, v35, v37
	v_add3_u32 v165, s10, v37, v35
	v_add3_u32 v169, s5, v37, v35
	v_mul_u32_u24_e32 v42, 0x880, v158
	v_add_u32_e32 v45, s10, v32
	s_movk_i32 s10, 0x80
	v_mul_u32_u24_e32 v51, 0x44, v115
	s_movk_i32 s12, 0x100
	v_mul_u32_u24_e32 v53, 0x84, v115
	v_lshlrev_b32_e32 v35, 5, v46
	v_lshl_add_u64 v[142:143], v[22:23], 0, v[26:27]
	v_lshl_add_u64 v[24:25], s[58:59], 0, v[118:119]
	v_lshl_add_u64 v[30:31], s[46:47], 0, v[118:119]
	v_lshl_add_u64 v[148:149], v[22:23], 0, v[28:29]
	v_add_u32_e32 v22, -1, v158
	v_bfe_u32 v121, v223, 6, 3
	s_mov_b32 s75, 0
	v_lshl_add_u32 v182, v223, 2, s74
	v_cmp_gt_u32_e64 s[4:5], 64, v223
	v_cmp_lt_u32_e64 s[6:7], 63, v223
	v_cmp_eq_u32_e64 s[8:9], 63, v240
	v_add_u32_e32 v186, 0xfd00, v185
	v_cmp_gt_u32_e64 s[10:11], s10, v223
	v_mul_u32_u24_e32 v209, 0x110, v115
	v_cmp_gt_u32_e64 s[12:13], s12, v223
	v_add_u32_e32 v210, v44, v114
	v_add_u32_e32 v227, v34, v32
	v_add_u32_e32 v230, v33, v26
	v_add_u32_e32 v231, v38, v26
	v_add_u32_e32 v232, v45, v26
	v_add_u32_e32 v236, v33, v28
	v_add_u32_e32 v237, v38, v28
	v_add_u32_e32 v238, v45, v28
	v_cndmask_b32_e64 v128, 0, 1.0, vcc
	v_lshl_add_u64 v[144:145], v[24:25], 0, v[26:27]
	v_lshl_add_u64 v[146:147], v[30:31], 0, v[26:27]
	v_lshl_add_u64 v[150:151], v[24:25], 0, v[28:29]
	v_lshl_add_u64 v[152:153], v[30:31], 0, v[28:29]
	v_cmp_lt_u32_e64 s[44:45], 6, v22
	v_and_b32_e32 v244, 8, v158
	v_cmp_ne_u32_e64 s[46:47], 0, v121
	v_add_u32_e32 v245, s74, v39
	s_movk_i32 s53, 0xd00
	s_mov_b32 s52, 0xbf1b4598
	v_add_u32_e32 v246, v49, v50
	v_add_u32_e32 v247, v208, v51
	v_add_u32_e32 v248, v49, v48
	v_add_u32_e32 v249, v47, v52
	v_add_u32_e32 v250, v47, v53
	v_add_u32_e32 v251, v221, v35
	v_add_u32_e32 v252, v41, v42
	s_mov_b32 s54, s2
	s_branch .LBB0_277
.LBB0_276:
	s_or_b64 exec, exec, s[58:59]
	s_waitcnt lgkmcnt(0)
	s_barrier
	s_nop 3
	ds_read_b128 v[18:21], v181
	ds_read_b128 v[22:25], v181 offset:16
	s_lshl_b64 s[54:55], s[54:55], 12
	s_lshl_b64 s[54:55], s[54:55], 1
	s_andn2_b64 vcc, exec, s[56:57]
	s_waitcnt lgkmcnt(1)
	v_cvt_pk_bf16_f32 v18, v18, v19
	v_cvt_pk_bf16_f32 v19, v20, v21
	s_waitcnt lgkmcnt(0)
	v_cvt_pk_bf16_f32 v20, v22, v23
	v_cvt_pk_bf16_f32 v21, v24, v25
	ds_write_b128 v117, v[18:21] offset:27648
	s_waitcnt lgkmcnt(0)
	s_barrier
	ds_read_b128 v[18:21], v214
	ds_read_b128 v[22:25], v214 offset:2304
	ds_read_b128 v[26:29], v213 offset:64768
	ds_read_b128 v[30:33], v213 offset:37120
	ds_read_b128 v[34:37], v216
	s_waitcnt lgkmcnt(2)
	v_mfma_f32_16x16x32_bf16 v[18:21], v[18:21], v[26:29], 0
	v_mfma_f32_16x16x32_bf16 v[22:25], v[22:25], v[26:29], 0
	ds_read_b128 v[26:29], v217 offset:2304
	ds_read_b128 v[38:41], v215 offset:64768
	ds_read_b128 v[46:49], v215 offset:37120
	s_waitcnt lgkmcnt(1)
	v_mfma_f32_16x16x32_bf16 v[18:21], v[34:37], v[38:41], v[18:21]
	ds_read_b128 v[34:37], v167
	v_mfma_f32_16x16x32_bf16 v[22:25], v[26:29], v[38:41], v[22:25]
	ds_read_b128 v[26:29], v167 offset:2304
	ds_read_b128 v[38:41], v168
	s_nop 3
	v_cvt_pk_bf16_f32 v18, v18, v19
	s_waitcnt lgkmcnt(2)
	v_mfma_f32_16x16x32_bf16 v[34:37], v[34:37], v[30:33], 0
	v_cvt_pk_bf16_f32 v19, v20, v21
	s_waitcnt lgkmcnt(1)
	v_mfma_f32_16x16x32_bf16 v[26:29], v[26:29], v[30:33], 0
	ds_read_b128 v[30:33], v169 offset:2304
	s_waitcnt lgkmcnt(1)
	v_mfma_f32_16x16x32_bf16 v[34:37], v[38:41], v[46:49], v[34:37]
	s_waitcnt lgkmcnt(0)
	v_mfma_f32_16x16x32_bf16 v[26:29], v[30:33], v[46:49], v[26:29]
	v_add_u32_e32 v30, 0x100, v233
	s_nop 4
	v_cvt_pk_bf16_f32 v20, v34, v35
	v_cvt_pk_bf16_f32 v21, v36, v37
	ds_write2st64_b64 v30, v[18:19], v[20:21] offset1:18
	v_cvt_pk_bf16_f32 v18, v22, v23
	v_cvt_pk_bf16_f32 v19, v24, v25
	v_cvt_pk_bf16_f32 v20, v26, v27
	v_cvt_pk_bf16_f32 v21, v28, v29
	v_add_u32_e32 v22, 0x100, v239
	ds_write2st64_b64 v22, v[18:19], v[20:21] offset1:18
	s_waitcnt lgkmcnt(0)
	s_barrier
; __device__ __forceinline__ float bflo(unsigned v) { return __uint_as_float(v << 16); }
; __device__ void rwkv_prep_item(const Params& p, char* lds_, int item, PrepRaw& raw, int next_item) {
;     ...
;   {
;     f32x4 a1[2]; zero2(a1);
;     mm_nt(X1T, TB, a1, wave, lane);
; #pragma unroll
;     for (int jj = 0; jj < 2; ++jj) {
;       const int j0 = (jt0 + jj) * 16 + 4 * mg;
;       u32x2 w; w.x = pk2(a1[jj][0], a1[jj][1]); w.y = pk2(a1[jj][2], a1[jj][3]); *(u32x2*)(U0T + mi * LD + j0) = w;
;     }
;   }
;   __syncthreads();
;   {
;     f32x4 pp[2], qt[2], ry[2], y0[2]; zero2(pp); zero2(qt); zero2(ry); zero2(y0);
;     mm_nt<true, false>(BT, WT, pp, wave, lane);
;     mm_nt<false, true>(U0T, BT, qt, wave, lane); mm_nt<true, true>(VT, KT, qt, wave, lane);
;     mm_nt(MRB, WT, ry, wave, lane);
;     ...
;     mm_nt<false, true>(MRK, VT, y0, wave, lane);
;     ...
;     mm_nt(MRB, U0T, y0, wave, lane);
;     ...
;     mm_nt(MRB, X1T, y0, wave, lane);
;     ...
;     mm_nt(MRB, VT, y0, wave, lane);
;     ...
;     mm_nt(MRK, U0T, y0, wave, lane);
;     ...
;     mm_nt(MRB, U0T, y0, wave, lane); mm_nt<false, true>(MRK, VT, y0, wave, lane);
;     ...
;     const float gci = gC[mi];
; #pragma unroll
;     for (int jj = 0; jj < 2; ++jj) {
;       const int jt = jt0 + jj, j0 = jt * 16 + 4 * mg;
;       float pv[4];
; #pragma unroll
;       for (int e = 0; e < 4; ++e) pv[e] = gci * (pp[jj][e] + ((j0 + e) == mi ? 1.f : 0.f));
;       u32x2 w; w.x = pk2(pv[0], pv[1]); w.y = pk2(pv[2], pv[3]);
;       *(u32x2*)(p.Pm + (size_t)item * 4096 + mi * 64 + (jt >> 1) * 32 + 8 * mg + 4 * (jt & 1)) = w;
;       const f32x4 gj = *(const f32x4*)(gC + j0);
;       { u32x2 qw; qw.x = pk2(qt[jj][0] * gj[0], qt[jj][1] * gj[1]); qw.y = pk2(qt[jj][2] * gj[2], qt[jj][3] * gj[3]);
;         *(u32x2*)(p.QT + (size_t)item * 4096 + mi * 64 + j0) = qw; }
;       const u32x2 rw = *(const u32x2*)(Rt + mi * LD + j0);
;       w.x = pk2(ry[jj][0] + bflo(rw.x), ry[jj][1] + bfhi(rw.x)); w.y = pk2(ry[jj][2] + bflo(rw.y), ry[jj][3] + bfhi(rw.y));
;       *(u32x2*)(p.Ry + (size_t)item * 4096 + mi * 64 + j0) = w;
;     ...
;       { const u32x2 dw = *(const u32x2*)(DBG_DUMP_SRC + mi * LD + j0); y0[jj][0] = bflo(dw.x); y0[jj][1] = bfhi(dw.x); y0[jj][2] = bflo(dw.y); y0[jj][3] = bfhi(dw.y); }
;     ...
;       { u32x2 yw; yw.x = pk2(y0[jj][0], y0[jj][1]); yw.y = pk2(y0[jj][2], y0[jj][3]);
;         *(u32x2*)(p.Y0 + (size_t)item * 4096 + mi * 64 + j0) = yw; }
;     }
;   }
	ds_read_b128 v[18:21], v167
	ds_read_b128 v[22:25], v167 offset:2304
	ds_read_b128 v[26:29], v187 offset:256
	ds_read_b128 v[30:33], v187 offset:320
	ds_read_b128 v[34:37], v168
	s_waitcnt lgkmcnt(2)
	v_mfma_f32_16x16x32_bf16 v[18:21], v[18:21], v[26:29], 0
	v_mfma_f32_16x16x32_bf16 v[22:25], v[22:25], v[26:29], 0
	ds_read_b128 v[26:29], v169 offset:2304
	s_waitcnt lgkmcnt(1)
	v_mfma_f32_16x16x32_bf16 v[18:21], v[34:37], v[30:33], v[18:21]
	s_waitcnt lgkmcnt(0)
	v_mfma_f32_16x16x32_bf16 v[22:25], v[26:29], v[30:33], v[22:25]
	s_nop 5
	v_cvt_pk_bf16_f32 v18, v18, v19
	v_cvt_pk_bf16_f32 v19, v20, v21
	v_add_u32_e32 v20, v221, v120
	ds_write_b64 v20, v[18:19] offset:18688
	v_cvt_pk_bf16_f32 v18, v22, v23
	v_cvt_pk_bf16_f32 v19, v24, v25
	ds_write_b64 v251, v[18:19] offset:18688
	s_waitcnt lgkmcnt(0)
	s_barrier
	ds_read_b128 v[18:21], v188 offset:9472
	ds_read_b128 v[22:25], v213 offset:46336
	ds_read_b128 v[26:29], v188 offset:9536
	ds_read_b128 v[30:33], v213 offset:64768
	ds_read_b128 v[38:41], v188 offset:11776
	ds_read_b128 v[46:49], v188 offset:11840
	ds_read_b128 v[50:53], v215 offset:46336
	ds_read_b128 v[54:57], v215 offset:64768
	ds_read_b128 v[58:61], v222 offset:46336
	s_waitcnt lgkmcnt(7)
	v_mfma_f32_16x16x32_bf16 v[34:37], v[18:21], v[22:25], 0
	s_waitcnt lgkmcnt(4)
	v_mfma_f32_16x16x32_bf16 v[22:25], v[38:41], v[22:25], 0
	s_waitcnt lgkmcnt(2)
	v_mfma_f32_16x16x32_bf16 v[34:37], v[26:29], v[50:53], v[34:37]
	v_mfma_f32_16x16x32_bf16 v[22:25], v[46:49], v[50:53], v[22:25]
	ds_read_b128 v[50:53], v187 offset:18688
	ds_read_b128 v[62:65], v187 offset:18752
	ds_read_b128 v[66:69], v222 offset:55552
	ds_read_b128 v[70:73], v224 offset:46336
	ds_read_b128 v[74:77], v222 offset:64768
	s_nop 1
	v_pk_add_f32 v[34:35], v[122:123], v[34:35]
	s_waitcnt lgkmcnt(4)
	v_mfma_f32_16x16x32_bf16 v[58:61], v[58:61], v[50:53], 0
	v_add_f32_e64 v36, v124, v36
	v_add_f32_e64 v37, v125, v37
	v_pk_add_f32 v[24:25], v[128:129], v[24:25]
	s_waitcnt lgkmcnt(1)
	v_mfma_f32_16x16x32_bf16 v[50:53], v[70:73], v[50:53], 0
	ds_read_b128 v[70:73], v225 offset:46336
	ds_read_b128 v[78:81], v225 offset:55552
	s_waitcnt lgkmcnt(1)
	v_mfma_f32_16x16x32_bf16 v[58:61], v[70:73], v[62:65], v[58:61]
	ds_read_b128 v[70:73], v226 offset:46336
	ds_read_b128 v[82:85], v225 offset:64768
	s_waitcnt lgkmcnt(1)
	v_mfma_f32_16x16x32_bf16 v[50:53], v[70:73], v[62:65], v[50:53]
	v_mfma_f32_16x16x32_bf16 v[58:61], v[66:69], v[30:33], v[58:61]
	ds_read_b128 v[62:65], v224 offset:55552
	ds_read_b128 v[66:69], v224 offset:64768
	s_waitcnt lgkmcnt(1)
	v_mfma_f32_16x16x32_bf16 v[30:33], v[62:65], v[30:33], v[50:53]
	v_mfma_f32_16x16x32_bf16 v[50:53], v[78:81], v[54:57], v[58:61]
	s_nop 2
	ds_read_b128 v[58:61], v226 offset:55552
	ds_read_b128 v[62:65], v226 offset:64768
	s_waitcnt lgkmcnt(1)
	v_mfma_f32_16x16x32_bf16 v[30:33], v[58:61], v[54:57], v[30:33]
	ds_read_b128 v[54:57], v166
	ds_read_b128 v[58:61], v166 offset:64
	ds_read_b128 v[70:73], v188 offset:20992
	s_waitcnt lgkmcnt(2)
	v_mfma_f32_16x16x32_bf16 v[18:21], v[18:21], v[54:57], 0
	s_waitcnt lgkmcnt(1)
	v_mfma_f32_16x16x32_bf16 v[18:21], v[26:29], v[58:61], v[18:21]
	ds_read_b128 v[26:29], v188 offset:18688
	v_mfma_f32_16x16x32_bf16 v[38:41], v[38:41], v[54:57], 0
	s_waitcnt lgkmcnt(0)
	v_mfma_f32_16x16x32_bf16 v[26:29], v[26:29], v[54:57], 0
	v_mfma_f32_16x16x32_bf16 v[38:41], v[46:49], v[58:61], v[38:41]
	ds_read_b128 v[46:49], v188 offset:18752
	ds_read_b128 v[78:81], v188 offset:21056
	ds_read_b32 v94, v228
	ds_read_b128 v[86:89], v227
	ds_read_b128 v[90:93], v227 offset:64
	s_waitcnt lgkmcnt(2)
	v_pk_mul_f32 v[34:35], v[34:35], v[94:95] op_sel_hi:[1,0]
	v_mfma_f32_16x16x32_bf16 v[26:29], v[46:49], v[58:61], v[26:29]
	ds_read_b128 v[46:49], v234
	v_pk_mul_f32 v[36:37], v[36:37], v[94:95] op_sel_hi:[1,0]
	v_pk_mul_f32 v[24:25], v[24:25], v[94:95] op_sel_hi:[1,0]
	v_mfma_f32_16x16x32_bf16 v[54:57], v[70:73], v[54:57], 0
	ds_read_b64 v[70:71], v233 offset:27904
	s_waitcnt lgkmcnt(1)
	v_pk_mul_f32 v[48:49], v[52:53], v[48:49]
	v_pk_mul_f32 v[46:47], v[50:51], v[46:47]
	v_mfma_f32_16x16x32_bf16 v[26:29], v[74:77], v[86:89], v[26:29]
	v_cvt_pk_bf16_f32 v72, v34, v35
	v_cvt_pk_bf16_f32 v73, v36, v37
	v_cvt_pk_bf16_f32 v46, v46, v47
	v_mfma_f32_16x16x32_bf16 v[34:37], v[78:81], v[58:61], v[54:57]
	v_cvt_pk_bf16_f32 v47, v48, v49
	v_lshl_add_u64 v[48:49], v[142:143], 0, s[54:55]
	s_nop 0
	v_lshl_add_u64 v[54:55], v[140:141], 0, s[54:55]
	global_store_dwordx2 v[54:55], v[72:73], off
	v_mfma_f32_16x16x32_bf16 v[26:29], v[82:85], v[90:93], v[26:29]
	global_store_dwordx2 v[48:49], v[46:47], off
	s_waitcnt lgkmcnt(0)
	v_lshlrev_b32_e32 v46, 16, v70
	v_and_b32_e32 v47, 0xffff0000, v70
	v_pk_add_f32 v[18:19], v[18:19], v[46:47]
	v_lshlrev_b32_e32 v46, 16, v71
	v_and_b32_e32 v47, 0xffff0000, v71
	v_pk_add_f32 v[20:21], v[20:21], v[46:47]
	v_cvt_pk_bf16_f32 v18, v18, v19
	v_cvt_pk_bf16_f32 v19, v20, v21
	v_lshl_add_u64 v[20:21], v[144:145], 0, s[54:55]
	global_store_dwordx2 v[20:21], v[18:19], off
	v_cvt_pk_bf16_f32 v18, v26, v27
	v_cvt_pk_bf16_f32 v19, v28, v29
	v_lshl_add_u64 v[20:21], v[146:147], 0, s[54:55]
	global_store_dwordx2 v[20:21], v[18:19], off
	v_pk_add_f32 v[18:19], v[126:127], v[22:23]
	ds_read_b64 v[56:57], v239 offset:27904
	v_pk_mul_f32 v[22:23], v[18:19], v[94:95] op_sel_hi:[1,0]
	ds_read_b128 v[18:21], v243
	v_mfma_f32_16x16x32_bf16 v[34:37], v[66:69], v[86:89], v[34:37]
	v_cvt_pk_bf16_f32 v22, v22, v23
	v_cvt_pk_bf16_f32 v23, v24, v25
	global_store_dwordx2 v[54:55], v[22:23], off offset:8
	s_waitcnt lgkmcnt(0)
	v_pk_mul_f32 v[20:21], v[32:33], v[20:21]
	v_pk_mul_f32 v[18:19], v[30:31], v[18:19]
	v_mfma_f32_16x16x32_bf16 v[34:37], v[62:65], v[90:93], v[34:37]
	v_cvt_pk_bf16_f32 v18, v18, v19
	v_cvt_pk_bf16_f32 v19, v20, v21
	v_lshl_add_u64 v[20:21], v[148:149], 0, s[54:55]
	global_store_dwordx2 v[20:21], v[18:19], off
	v_lshlrev_b32_e32 v18, 16, v56
	v_and_b32_e32 v19, 0xffff0000, v56
	v_lshlrev_b32_e32 v20, 16, v57
	v_and_b32_e32 v21, 0xffff0000, v57
	v_pk_add_f32 v[18:19], v[38:39], v[18:19]
	v_pk_add_f32 v[20:21], v[40:41], v[20:21]
	v_cvt_pk_bf16_f32 v18, v18, v19
	v_cvt_pk_bf16_f32 v19, v20, v21
	v_lshl_add_u64 v[20:21], v[150:151], 0, s[54:55]
	global_store_dwordx2 v[20:21], v[18:19], off
	v_cvt_pk_bf16_f32 v18, v34, v35
	v_cvt_pk_bf16_f32 v19, v36, v37
	v_lshl_add_u64 v[20:21], v[152:153], 0, s[54:55]
	global_store_dwordx2 v[20:21], v[18:19], off
	s_waitcnt vmcnt(11)
	v_mov_b64_e32 v[18:19], v[42:43]
	s_mov_b32 s54, s90
	v_mov_b64_e32 v[20:21], v[44:45]
	s_cbranch_vccz .LBB0_329
; __device__ void rwkv_prep_item(const Params& p, char* lds_, int item, PrepRaw& raw, int next_item) {
;     ...
;   {
;     const int cbp = hd * 64 + cg8;
; #pragma unroll
;     for (int q = 0; q < 2; ++q) {
;       pdb[q] = *(const f32x4*)(p.decay_bias + cbp + 4 * q); pib[q] = *(const f32x4*)(p.iclr_bias + cbp + 4 * q);
;       pkk[q] = *(const f32x4*)(p.k_k + cbp + 4 * q); pka[q] = *(const f32x4*)(p.k_a + cbp + 4 * q); prk[q] = *(const f32x4*)(p.r_k + cbp + 4 * q);
;     }
;   }
;   __syncthreads();
;   {
;     auto ldshift = [&](int col, float (&o)[8], const u32x4 cur) {
;       u32x4 prv; prv.x = prv.y = prv.z = prv.w = 0u;
;       if (hasprev) prv = *(const u32x4*)(prow - PBW + col);
;     ...
;     *(u32x4*)(DUs + t * LD + cg8) = *(const u32x4*)(p.DUt + (size_t)(hd * 64 + t) * 64 + cg8);
;     *(u32x4*)(IUs + t * LD + cg8) = *(const u32x4*)(p.IUt + (size_t)(hd * 64 + t) * 64 + cg8);
.LBB0_277:
	s_and_b32 s55, s54, 0x1c0
	v_or_b32_e32 v23, s55, v116
	v_lshlrev_b32_e32 v22, 2, v23
	global_load_dwordx4 v[34:37], v22, s[62:63] offset:16
	global_load_dwordx4 v[38:41], v22, s[62:63]
	global_load_dwordx4 v[54:57], v22, s[80:81] offset:16
	global_load_dwordx4 v[70:73], v22, s[80:81]
	global_load_dwordx4 v[46:49], v22, s[64:65] offset:16
	global_load_dwordx4 v[50:53], v22, s[66:67] offset:16
	global_load_dwordx4 v[66:69], v22, s[64:65]
	global_load_dwordx4 v[62:65], v22, s[66:67]
	global_load_dwordx4 v[42:45], v22, s[82:83] offset:16
	global_load_dwordx4 v[58:61], v22, s[82:83]
	v_add_lshl_u32 v192, s55, v240, 7
	v_mov_b32_e32 v193, 0
	v_mov_b64_e32 v[158:159], v[192:193]
	v_lshl_add_u64 v[192:193], v[136:137], 0, v[192:193]
	global_load_dwordx4 v[192:195], v[192:193], off
	v_lshl_add_u64 v[158:159], v[134:135], 0, v[158:159]
	global_load_dwordx4 v[158:161], v[158:159], off
	global_load_dwordx4 v[196:199], v[132:133], off offset:16
	global_load_dwordx4 v[200:203], v[132:133], off
	s_lshl_b32 s57, s54, 6
	s_ashr_i32 s56, s54, 9
	s_and_b32 s57, s57, 0xfc0
	v_add_u32_e32 v118, s57, v240
	s_ashr_i32 s57, s56, 31
	s_lshl_b64 s[56:57], s[56:57], 12
	v_lshl_add_u64 v[24:25], s[56:57], 0, v[118:119]
	v_mov_b64_e32 v[26:27], s[78:79]
	v_mad_u64_u32 v[156:157], s[56:57], v24, s53, v[26:27]
	v_mad_i32_i24 v157, v25, s53, v157
	v_cmp_ne_u32_e32 vcc, 0, v118
	v_lshlrev_b32_e32 v118, 1, v23
	v_mov_b32_e32 v78, 0
	v_mov_b32_e32 v79, 0
	v_mov_b32_e32 v80, 0
	v_mov_b32_e32 v81, 0
	s_barrier
	s_and_saveexec_b64 s[56:57], vcc
	s_cbranch_execz .LBB0_279
	v_lshl_add_u64 v[24:25], v[156:157], 0, v[118:119]
	global_load_dwordx4 v[78:81], v[24:25], off offset:-3328

; __device__ __forceinline__ unsigned pk2(float lo, float hi) { f32x2_t v = {lo, hi}; bf16x2_t b = __builtin_convertvector(v, bf16x2_t); return __builtin_bit_cast(unsigned, b); }
; __device__ __forceinline__ float bflo(unsigned v) { return __uint_as_float(v << 16); }
; __device__ __forceinline__ float bfhi(unsigned v) { return __uint_as_float(v & 0xffff0000u); }
; __device__ __forceinline__ float fexp(float x) { return __builtin_amdgcn_exp2f(x * 1.44269504088896f); }
; __device__ void rwkv_prep_item(const Params& p, char* lds_, int item, PrepRaw& raw, int next_item) {
;     ...
;     auto ldshift = [&](int col, float (&o)[8], const u32x4 cur) {
;       u32x4 prv; prv.x = prv.y = prv.z = prv.w = 0u;
;       if (hasprev) prv = *(const u32x4*)(prow - PBW + col);
;       const f32x4 m0 = *(const f32x4*)(p.shift_mu + col), m1 = *(const f32x4*)(p.shift_mu + col + 4);
;       const unsigned cw[4] = {cur.x, cur.y, cur.z, cur.w}, pw[4] = {prv.x, prv.y, prv.z, prv.w};
; #pragma unroll
;       for (int q = 0; q < 4; ++q) {
;         const float c0 = bflo(cw[q]), c1 = bfhi(cw[q]), p0 = bflo(pw[q]), p1 = bfhi(pw[q]);
;         const float mu0 = (q < 2) ? m0[2 * q] : m1[2 * q - 4], mu1 = (q < 2) ? m0[2 * q + 1] : m1[2 * q - 3];
;         o[2 * q] = c0 + (p0 - c0) * mu0;
;         o[2 * q + 1] = c1 + (p1 - c1) * mu1;
;       }
;     };
;     ldshift(hd * 64 + cg8, rr, raw.cur[0]);
;     ldshift(512 + hd * 64 + cg8, kk_, raw.cur[1]);
;     ldshift(1024 + hd * 64 + cg8, vv, raw.cur[2]);
;     float wd[8], ad[8];
;     ldshift(1536 + cg8, wd, raw.cur[3]);
;     ldshift(1600 + cg8, ad, raw.cur[4]);
;     u32x4 w;
;     float th[8];
; #pragma unroll
;     for (int e = 0; e < 8; ++e) th[e] = 1.f - 2.f * __builtin_amdgcn_rcpf(1.f + fexp(2.f * wd[e]));
;     w.x = pk2(th[0], th[1]); w.y = pk2(th[2], th[3]); w.z = pk2(th[4], th[5]); w.w = pk2(th[6], th[7]);
;     *(u32x4*)(TW + t * LD + cg8) = w;
;     w.x = pk2(ad[0], ad[1]); w.y = pk2(ad[2], ad[3]); w.z = pk2(ad[4], ad[5]); w.w = pk2(ad[6], ad[7]);
;     *(u32x4*)(AD + t * LD + cg8) = w;
;     *(u32x4*)(DUs + t * LD + cg8) = *(const u32x4*)(p.DUt + (size_t)(hd * 64 + t) * 64 + cg8);
;     *(u32x4*)(IUs + t * LD + cg8) = *(const u32x4*)(p.IUt + (size_t)(hd * 64 + t) * 64 + cg8);
.LBB0_291:
	s_or_b64 exec, exec, s[56:57]
	s_waitcnt vmcnt(19)
	v_lshlrev_b32_e32 v118, 16, v10
	v_and_b32_e32 v155, 0xffff0000, v10
	s_waitcnt vmcnt(2)
	v_lshlrev_b32_e32 v156, 16, v102
	v_and_b32_e32 v102, 0xffff0000, v102
	v_sub_f32_e32 v156, v156, v118
	v_sub_f32_e32 v102, v102, v155
	s_waitcnt vmcnt(0)
	v_fmac_f32_e32 v118, v110, v156
	v_fmac_f32_e32 v155, v111, v102
	v_lshlrev_b32_e32 v110, 16, v11
	v_lshlrev_b32_e32 v102, 16, v103
	v_and_b32_e32 v111, 0xffff0000, v11
	v_and_b32_e32 v103, 0xffff0000, v103
	v_sub_f32_e32 v102, v102, v110
	v_fmac_f32_e32 v110, v112, v102
	v_sub_f32_e32 v102, v103, v111
	v_fmac_f32_e32 v111, v113, v102
	v_lshlrev_b32_e32 v112, 16, v12
	v_lshlrev_b32_e32 v102, 16, v104
	v_and_b32_e32 v113, 0xffff0000, v12
	v_and_b32_e32 v103, 0xffff0000, v104
	v_sub_f32_e32 v102, v102, v112
	v_fmac_f32_e32 v112, v106, v102
	v_sub_f32_e32 v102, v103, v113
	v_fmac_f32_e32 v113, v107, v102
	v_and_b32_e32 v102, 0xffff0000, v105
	v_and_b32_e32 v156, 0xffff0000, v13
	v_sub_f32_e32 v102, v102, v156
	v_lshlrev_b32_e32 v103, 16, v105
	v_lshlrev_b32_e32 v157, 16, v13
	v_fmac_f32_e32 v156, v109, v102
	v_and_b32_e32 v104, 0xffff0000, v2
	v_lshlrev_b32_e32 v102, 16, v90
	v_and_b32_e32 v90, 0xffff0000, v90
	v_sub_f32_e32 v103, v103, v157
	v_lshlrev_b32_e32 v105, 16, v2
	v_sub_f32_e32 v90, v90, v104
	v_fmac_f32_e32 v157, v108, v103
	v_sub_f32_e32 v102, v102, v105
	v_fmac_f32_e32 v104, v99, v90
	v_lshlrev_b32_e32 v103, 16, v3
	v_lshlrev_b32_e32 v90, 16, v91
	v_fmac_f32_e32 v105, v98, v102
	v_and_b32_e32 v102, 0xffff0000, v3
	v_and_b32_e32 v91, 0xffff0000, v91
	v_sub_f32_e32 v90, v90, v103
	v_fmac_f32_e32 v103, v100, v90
	v_sub_f32_e32 v90, v91, v102
	v_fmac_f32_e32 v102, v101, v90
	v_lshlrev_b32_e32 v99, 16, v4
	v_lshlrev_b32_e32 v90, 16, v92
	v_and_b32_e32 v98, 0xffff0000, v4
	v_and_b32_e32 v91, 0xffff0000, v92
	v_sub_f32_e32 v90, v90, v99
	v_fmac_f32_e32 v99, v94, v90
	v_sub_f32_e32 v90, v91, v98
	v_fmac_f32_e32 v98, v95, v90
	v_and_b32_e32 v90, 0xffff0000, v93
	v_and_b32_e32 v92, 0xffff0000, v5
	v_lshlrev_b32_e32 v91, 16, v93
	v_lshlrev_b32_e32 v93, 16, v5
	v_sub_f32_e32 v90, v90, v92
	v_sub_f32_e32 v91, v91, v93
	v_fmac_f32_e32 v92, v97, v90
	v_and_b32_e32 v90, 0xffff0000, v6
	v_lshlrev_b32_e32 v94, 16, v78
	v_and_b32_e32 v78, 0xffff0000, v78
	v_fmac_f32_e32 v93, v96, v91
	v_lshlrev_b32_e32 v91, 16, v6
	v_sub_f32_e32 v78, v78, v90
	v_sub_f32_e32 v94, v94, v91
	v_fmac_f32_e32 v90, v87, v78
	v_lshlrev_b32_e32 v87, 16, v7
	v_lshlrev_b32_e32 v78, 16, v79
	v_fmac_f32_e32 v91, v86, v94
	v_and_b32_e32 v86, 0xffff0000, v7
	v_and_b32_e32 v79, 0xffff0000, v79
	v_sub_f32_e32 v78, v78, v87
	v_fmac_f32_e32 v87, v88, v78
	v_sub_f32_e32 v78, v79, v86
	v_fmac_f32_e32 v86, v89, v78
	v_lshlrev_b32_e32 v89, 16, v8
	v_lshlrev_b32_e32 v78, 16, v80
	v_and_b32_e32 v88, 0xffff0000, v8
	v_and_b32_e32 v79, 0xffff0000, v80
	v_sub_f32_e32 v78, v78, v89
	v_fmac_f32_e32 v89, v78, v82
	v_sub_f32_e32 v78, v79, v88
	v_fmac_f32_e32 v88, v78, v83
	v_and_b32_e32 v78, 0xffff0000, v81
	v_lshlrev_b32_e32 v79, 16, v81
	v_and_b32_e32 v82, 0xffff0000, v9
	v_lshlrev_b32_e32 v83, 16, v9
	v_sub_f32_e32 v79, v79, v83
	v_sub_f32_e32 v78, v78, v82
	v_fmac_f32_e32 v83, v79, v84
	v_fmac_f32_e32 v82, v78, v85
	v_add_f32_e32 v84, v118, v118
	v_add_f32_e32 v85, v155, v155
	v_add_f32_e32 v100, v110, v110
	v_add_f32_e32 v101, v111, v111
	v_add_f32_e32 v106, v112, v112
	v_add_f32_e32 v107, v113, v113
	v_add_f32_e32 v108, v157, v157
	v_add_f32_e32 v109, v156, v156
	v_mul_f32_e32 v84, 0x3fb8aa3b, v84
	v_mul_f32_e32 v85, 0x3fb8aa3b, v85
	v_mul_f32_e32 v100, 0x3fb8aa3b, v100
	v_mul_f32_e32 v101, 0x3fb8aa3b, v101
	v_mul_f32_e32 v106, 0x3fb8aa3b, v106
	v_mul_f32_e32 v107, 0x3fb8aa3b, v107
	v_mul_f32_e32 v108, 0x3fb8aa3b, v108
	v_mul_f32_e32 v109, 0x3fb8aa3b, v109
	v_exp_f32_e32 v84, v84
	v_exp_f32_e32 v85, v85
	v_exp_f32_e32 v100, v100
	v_exp_f32_e32 v101, v101
	v_exp_f32_e32 v106, v106
	v_exp_f32_e32 v107, v107
	v_exp_f32_e32 v108, v108
	v_exp_f32_e32 v109, v109
	v_lshlrev_b32_e32 v110, 16, v14
	v_and_b32_e32 v111, 0xffff0000, v14
	v_lshlrev_b32_e32 v112, 16, v74
	v_and_b32_e32 v113, 0xffff0000, v74
	v_pk_add_f32 v[112:113], v[112:113], v[110:111] neg_lo:[0,1] neg_hi:[0,1]
	v_add_f32_e32 v84, 1.0, v84
	v_add_f32_e32 v85, 1.0, v85
	v_add_f32_e32 v100, 1.0, v100
	v_add_f32_e32 v101, 1.0, v101
	v_add_f32_e32 v106, 1.0, v106
	v_add_f32_e32 v107, 1.0, v107
	v_add_f32_e32 v108, 1.0, v108
	v_add_f32_e32 v109, 1.0, v109
	v_lshlrev_b32_e32 v74, 16, v75
	v_and_b32_e32 v75, 0xffff0000, v75
	v_rcp_f32_e32 v84, v84
	v_rcp_f32_e32 v85, v85
	v_rcp_f32_e32 v100, v100
	v_rcp_f32_e32 v101, v101
	v_rcp_f32_e32 v106, v106
	v_rcp_f32_e32 v107, v107
	v_rcp_f32_e32 v108, v108
	v_rcp_f32_e32 v109, v109
	v_pk_fma_f32 v[84:85], v[84:85], 2.0, 1.0 op_sel_hi:[1,0,0] neg_lo:[1,0,0] neg_hi:[1,0,0]
	v_pk_fma_f32 v[100:101], v[100:101], 2.0, 1.0 op_sel_hi:[1,0,0] neg_lo:[1,0,0] neg_hi:[1,0,0]
	v_pk_fma_f32 v[106:107], v[106:107], 2.0, 1.0 op_sel_hi:[1,0,0] neg_lo:[1,0,0] neg_hi:[1,0,0]
	v_pk_fma_f32 v[108:109], v[108:109], 2.0, 1.0 op_sel_hi:[1,0,0] neg_lo:[1,0,0] neg_hi:[1,0,0]
	v_add_lshl_u32 v118, s55, v240, 7
	v_mul_f32_e32 v67, v67, v104
	v_mul_f32_e32 v66, v66, v105
	v_mul_f32_e32 v68, v68, v103
	v_mul_f32_e32 v69, v69, v102
	s_add_i32 s90, s54, s50
	s_waitcnt vmcnt(0)
	v_pk_fma_f32 v[94:95], v[200:201], v[112:113], v[110:111]
	v_lshlrev_b32_e32 v110, 16, v15
	v_and_b32_e32 v111, 0xffff0000, v15
	v_pk_add_f32 v[74:75], v[74:75], v[110:111] neg_lo:[0,1] neg_hi:[0,1]
	s_nop 0
	v_pk_fma_f32 v[96:97], v[202:203], v[74:75], v[110:111]
	v_lshlrev_b32_e32 v74, 16, v16
	v_and_b32_e32 v75, 0xffff0000, v16
	v_lshlrev_b32_e32 v110, 16, v76
	v_and_b32_e32 v111, 0xffff0000, v76
	v_pk_add_f32 v[110:111], v[110:111], v[74:75] neg_lo:[0,1] neg_hi:[0,1]
	v_lshlrev_b32_e32 v76, 16, v17
	v_pk_fma_f32 v[78:79], v[196:197], v[110:111], v[74:75]
	v_lshlrev_b32_e32 v74, 16, v77
	v_and_b32_e32 v75, 0xffff0000, v77
	v_and_b32_e32 v77, 0xffff0000, v17
	v_pk_add_f32 v[74:75], v[74:75], v[76:77] neg_lo:[0,1] neg_hi:[0,1]
	s_nop 0
	v_pk_fma_f32 v[80:81], v[198:199], v[74:75], v[76:77]
	v_cvt_pk_bf16_f32 v74, v84, v85
	v_cvt_pk_bf16_f32 v75, v100, v101
	v_cvt_pk_bf16_f32 v76, v106, v107
	v_cvt_pk_bf16_f32 v77, v108, v109
	ds_write_b128 v117, v[74:77]
	v_cvt_pk_bf16_f32 v74, v94, v95
	v_cvt_pk_bf16_f32 v75, v96, v97
	v_cvt_pk_bf16_f32 v76, v78, v79
	v_cvt_pk_bf16_f32 v77, v80, v81
	ds_write_b128 v117, v[74:77] offset:9216
	v_mul_f32_e32 v85, v67, v67
	v_fmac_f32_e32 v85, v66, v66
	v_fmac_f32_e32 v85, v68, v68
	v_fmac_f32_e32 v85, v69, v69
	ds_write_b128 v117, v[158:161] offset:18432
	ds_write_b128 v117, v[192:195] offset:27648
	s_waitcnt lgkmcnt(0)
	s_barrier
; __device__ __forceinline__ float fsigmoid(float x) { return __builtin_amdgcn_rcpf(1.f + fexp(-x)); }
; __device__ void rwkv_prep_item(const Params& p, char* lds_, int item, PrepRaw& raw, int next_item) {
;     ...
;   const int it = wave >> 1, jt0 = (wave & 1) * 2, mr = lane & 15, mg = lane >> 4;
;   const int mi = it * 16 + mr;
;   {
;     f32x4 a1[2], a2[2]; zero2(a1); zero2(a2);
;     mm_nt(TW, DUs, a1, wave, lane);
;     mm_nt(AD, IUs, a2, wave, lane);
; #pragma unroll
;     for (int jj = 0; jj < 2; ++jj) {
;       *(f32x4*)(Zw + mi * 68 + (jt0 + jj) * 16 + 4 * mg) = a1[jj];
;       *(f32x4*)(Za + mi * 68 + (jt0 + jj) * 16 + 4 * mg) = a2[jj];
;     }
;   }
;   __syncthreads();
;   float av[8], bv[8], k2[8], lw[8];
;   float bon;
;   {
;     float ss = 0.f; bon = 0.f;
;     float kk[8], ai[8];
; #pragma unroll
;     for (int e = 0; e < 8; ++e) {
;       const float zw = Zw[t * 68 + cg8 + e] + pdb[e >> 2][e & 3];
;       const float za = Za[t * 68 + cg8 + e] + pib[e >> 2][e & 3];
;       lw[e] = -0.6065306597126334f * fsigmoid(zw);
;       ai[e] = fsigmoid(za);
;       kk[e] = kk_[e] * pkk[e >> 2][e & 3];
;       k2[e] = kk_[e] * (1.f + (ai[e] - 1.f) * pka[e >> 2][e & 3]);
;       ss += kk[e] * kk[e];
;       bon += rr[e] * k2[e] * prk[e >> 2][e & 3];
;     }
;     ss += __shfl_xor(ss, 1); ss += __shfl_xor(ss, 2); ss += __shfl_xor(ss, 4);
;     bon += __shfl_xor(bon, 1); bon += __shfl_xor(bon, 2); bon += __shfl_xor(bon, 4);
;     const float inv = __builtin_amdgcn_rsqf(fmaxf(ss, 1e-24f));
; #pragma unroll
;     for (int e = 0; e < 8; ++e) { const float kn = kk[e] * inv; av[e] = -kn; bv[e] = kn * ai[e]; }
;   }
;   __builtin_amdgcn_sched_barrier(0);
;   if (next_item < 4096) prep_load(p, next_item, raw);
	ds_read_b128 v[74:77], v162
	ds_read_b128 v[78:81], v163
	ds_read_b128 v[94:97], v163 offset:2304
	s_waitcnt lgkmcnt(1)
	v_mfma_f32_16x16x32_bf16 v[78:81], v[78:81], v[74:77], 0
	s_waitcnt lgkmcnt(0)
	v_mfma_f32_16x16x32_bf16 v[74:77], v[94:97], v[74:77], 0
	ds_read_b128 v[94:97], v162 offset:64
	ds_read_b128 v[106:109], v164
	s_waitcnt lgkmcnt(0)
	v_mfma_f32_16x16x32_bf16 v[78:81], v[106:109], v[94:97], v[78:81]
	ds_read_b128 v[106:109], v165 offset:2304
	s_waitcnt lgkmcnt(0)
	v_mfma_f32_16x16x32_bf16 v[74:77], v[106:109], v[94:97], v[74:77]
	ds_read_b128 v[94:97], v166
	ds_read_b128 v[106:109], v167
	ds_read_b128 v[110:113], v167 offset:2304
	s_waitcnt lgkmcnt(1)
	v_mfma_f32_16x16x32_bf16 v[106:109], v[106:109], v[94:97], 0
	s_waitcnt lgkmcnt(0)
	v_mfma_f32_16x16x32_bf16 v[94:97], v[110:113], v[94:97], 0
	ds_read_b128 v[110:113], v166 offset:64
	ds_read_b128 v[192:195], v168
	s_waitcnt lgkmcnt(0)
	v_mfma_f32_16x16x32_bf16 v[106:109], v[192:195], v[110:113], v[106:109]
	ds_read_b128 v[192:195], v169 offset:2304
	s_waitcnt lgkmcnt(0)
	v_mfma_f32_16x16x32_bf16 v[94:97], v[192:195], v[110:113], v[94:97]
	ds_write_b128 v170, v[78:81]
	s_nop 3
	ds_write_b128 v171, v[106:109]
	ds_write_b128 v170, v[74:77] offset:64
	s_nop 0
	ds_write_b128 v171, v[94:97] offset:64
	s_waitcnt lgkmcnt(0)
	s_barrier
	ds_read_b128 v[74:77], v172
	ds_read_b128 v[78:81], v173
	s_waitcnt lgkmcnt(0)
	v_add_f32_e32 v70, v70, v78
	v_mul_f32_e32 v70, 0xbfb8aa3b, v70
	v_exp_f32_e32 v70, v70
	s_nop 0
	v_add_f32_e32 v70, 1.0, v70
	v_rcp_f32_e32 v70, v70
	s_nop 0
	v_add_f32_e32 v78, -1.0, v70
	v_fma_f32 v62, v62, v78, 1.0
	v_mul_f32_e32 v62, v105, v62
	v_mul_f32_e32 v78, v91, v62
	v_fma_f32 v84, v58, v78, 0
	v_add_f32_e32 v58, v71, v79
	v_mul_f32_e32 v58, 0xbfb8aa3b, v58
	v_exp_f32_e32 v58, v58
	s_nop 0
	v_add_f32_e32 v58, 1.0, v58
	v_rcp_f32_e32 v71, v58
	s_nop 0
	v_add_f32_e32 v58, -1.0, v71
	v_fma_f32 v58, v63, v58, 1.0
	v_mul_f32_e32 v63, v104, v58
	v_mul_f32_e32 v58, v90, v63
	v_fmac_f32_e32 v84, v59, v58
	v_add_f32_e32 v58, v72, v80
	v_mul_f32_e32 v58, 0xbfb8aa3b, v58
	v_exp_f32_e32 v58, v58
	s_nop 0
	v_add_f32_e32 v58, 1.0, v58
	v_rcp_f32_e32 v72, v58
	s_nop 0
	v_add_f32_e32 v58, -1.0, v72
	v_fma_f32 v58, v64, v58, 1.0
	v_mul_f32_e32 v64, v103, v58
	v_mul_f32_e32 v58, v87, v64
	v_fmac_f32_e32 v84, v60, v58
	v_add_f32_e32 v58, v73, v81
	v_mul_f32_e32 v58, 0xbfb8aa3b, v58
	v_exp_f32_e32 v58, v58
	s_nop 0
	v_add_f32_e32 v58, 1.0, v58
	v_rcp_f32_e32 v73, v58
	s_nop 0
	v_add_f32_e32 v58, -1.0, v73
	v_fma_f32 v58, v65, v58, 1.0
	v_mul_f32_e32 v65, v102, v58
	v_mul_f32_e32 v58, v86, v65
	v_fmac_f32_e32 v84, v61, v58
	ds_read_b128 v[58:61], v176
	ds_read_b128 v[78:81], v177
	s_waitcnt lgkmcnt(0)
	v_add_f32_e32 v54, v54, v78
	v_mul_f32_e32 v54, 0xbfb8aa3b, v54
	v_exp_f32_e32 v54, v54
	v_mul_f32_e32 v78, v46, v99
	v_fmac_f32_e32 v85, v78, v78
	v_add_f32_e32 v54, 1.0, v54
	v_rcp_f32_e32 v54, v54
	s_nop 0
	v_add_f32_e32 v46, -1.0, v54
	v_fma_f32 v46, v50, v46, 1.0
	v_mul_f32_e32 v46, v99, v46
	v_mul_f32_e32 v50, v89, v46
	v_fmac_f32_e32 v84, v42, v50
	v_add_f32_e32 v42, v55, v79
	v_mul_f32_e32 v42, 0xbfb8aa3b, v42
	v_exp_f32_e32 v42, v42
	v_mul_f32_e32 v55, v47, v98
	v_fmac_f32_e32 v85, v55, v55
	v_mul_f32_e32 v79, v49, v92
	v_add_f32_e32 v42, 1.0, v42
	v_rcp_f32_e32 v50, v42
	s_nop 0
	v_add_f32_e32 v42, -1.0, v50
	v_fma_f32 v42, v51, v42, 1.0
	v_mul_f32_e32 v47, v98, v42
	v_mul_f32_e32 v42, v88, v47
	v_fmac_f32_e32 v84, v43, v42
	v_add_f32_e32 v42, v56, v80
	v_mul_f32_e32 v42, 0xbfb8aa3b, v42
	v_exp_f32_e32 v42, v42
	v_mul_f32_e32 v56, v48, v93
	v_fmac_f32_e32 v85, v56, v56
	v_fmac_f32_e32 v85, v79, v79
	v_add_f32_e32 v42, 1.0, v42
	v_rcp_f32_e32 v51, v42
	s_nop 0
	v_add_f32_e32 v42, -1.0, v51
	v_fma_f32 v42, v52, v42, 1.0
	v_mul_f32_e32 v52, v93, v42
	v_mul_f32_e32 v42, v83, v52
	v_fmac_f32_e32 v84, v44, v42
	v_add_f32_e32 v42, v57, v81
	v_mul_f32_e32 v42, 0xbfb8aa3b, v42
	v_exp_f32_e32 v42, v42
	s_nop 0
	v_add_f32_e32 v42, 1.0, v42
	v_rcp_f32_e32 v57, v42
	s_nop 0
	v_add_f32_e32 v42, -1.0, v57
	v_fma_f32 v42, v53, v42, 1.0
	v_mul_f32_e32 v53, v92, v42
	v_mul_f32_e32 v42, v82, v53
	v_fmac_f32_e32 v84, v45, v42
	ds_bpermute_b32 v42, v178, v85
	s_waitcnt lgkmcnt(0)
	v_add_f32_e32 v42, v85, v42
	ds_bpermute_b32 v43, v179, v42
	s_waitcnt lgkmcnt(0)
	v_add_f32_e32 v80, v42, v43
	ds_bpermute_b32 v42, v178, v84
	ds_bpermute_b32 v81, v180, v80
	s_waitcnt lgkmcnt(1)
	v_add_f32_e32 v42, v84, v42
	ds_bpermute_b32 v43, v179, v42
	s_waitcnt lgkmcnt(0)
	v_add_f32_e32 v48, v42, v43
	ds_bpermute_b32 v49, v180, v48
	s_cmpk_gt_i32 s90, 0xfff
	s_cselect_b64 s[56:57], -1, 0
	v_mov_b64_e32 v[44:45], v[20:21]
	s_and_b64 vcc, exec, s[56:57]
	v_mov_b64_e32 v[42:43], v[18:19]
	s_cbranch_vccnz .LBB0_293
	s_ashr_i32 s58, s90, 9
	s_lshl_b32 s74, s90, 6
	s_ashr_i32 s59, s58, 31
	s_and_b32 s74, s74, 0xfc0
	s_lshl_b64 s[58:59], s[58:59], 12
	v_add_u32_e32 v118, s74, v240
	v_lshl_add_u64 v[2:3], s[58:59], 0, v[118:119]
	v_mov_b64_e32 v[4:5], s[78:79]
	s_and_b32 s55, s90, 0x1c0
	v_mad_u64_u32 v[10:11], s[58:59], v2, s53, v[4:5]
	v_mad_i32_i24 v11, v3, s53, v11
	s_lshl_b32 s74, s55, 1
	v_lshl_add_u64 v[2:3], v[10:11], 0, s[74:75]
	v_mov_b32_e32 v155, v119
	v_lshl_add_u64 v[12:13], v[2:3], 0, v[154:155]
	v_lshl_add_u64 v[14:15], v[10:11], 0, v[154:155]
	global_load_dwordx4 v[6:9], v[12:13], off
	global_load_dwordx4 v[2:5], v[12:13], off offset:1024
	global_load_dwordx4 v[42:45], v[12:13], off offset:2048
	s_nop 0
	global_load_dwordx4 v[10:13], v[14:15], off offset:3072
	s_nop 0
	global_load_dwordx4 v[14:17], v[14:15], off offset:3200

; __device__ __forceinline__ unsigned pk2(float lo, float hi) { f32x2_t v = {lo, hi}; bf16x2_t b = __builtin_convertvector(v, bf16x2_t); return __builtin_bit_cast(unsigned, b); }
; __device__ void rwkv_prep_item(const Params& p, char* lds_, int item, PrepRaw& raw, int next_item) {
;     ...
;     put(At, AT, a_); put(Bt, BT, b_); put(Kt, KT, k_); put(Rt, nullptr, r_); put(nullptr, VT, vv);
;     u32x4 w;
;     w.x = pk2(bon * vv[0], bon * vv[1]); w.y = pk2(bon * vv[2], bon * vv[3]); w.z = pk2(bon * vv[4], bon * vv[5]); w.w = pk2(bon * vv[6], bon * vv[7]);
;     *(u32x4*)(p.BV + (size_t)item * 4096 + t * 64 + cg8) = w;
;   }
;   __syncthreads();
;   {
;     f32x4 lab[2], lak[2], mrb[2], mrk[2]; zero2(lab); zero2(lak); zero2(mrb); zero2(mrk);
;     mm_nt(At, Bt, lab, wave, lane);
;     mm_nt(At, Kt, lak, wave, lane);
;     mm_nt(Rt, Bt, mrb, wave, lane);
;     mm_nt(Rt, Kt, mrk, wave, lane);
; #pragma unroll
;     for (int jj = 0; jj < 2; ++jj) {
;       const int j0 = (jt0 + jj) * 16 + 4 * mg;
;       f32x4 o; float x1[4], x2[4], x3[4];
; #pragma unroll
;       for (int e = 0; e < 4; ++e) {
;         const int j = j0 + e;
;         o[e] = (j < mi) ? lab[jj][e] : 0.f;
;         x1[e] = (j < mi) ? lak[jj][e] : 0.f;
;         x2[e] = (j <= mi) ? mrb[jj][e] : 0.f;
;         x3[e] = (j <= mi) ? mrk[jj][e] : 0.f;
;       }
;       *(f32x4*)(Tf + mi * 68 + j0) = o;
;       u32x2 w;
;       w.x = pk2(x1[0], x1[1]); w.y = pk2(x1[2], x1[3]); *(u32x2*)(LAK + mi * LD + j0) = w;
;       w.x = pk2(x2[0], x2[1]); w.y = pk2(x2[2], x2[3]); *(u32x2*)(MRB + mi * LD + j0) = w;
;       w.x = pk2(x3[0], x3[1]); w.y = pk2(x3[2], x3[3]); *(u32x2*)(MRK + mi * LD + j0) = w;
;     }
;   }
;   __syncthreads();
;   {
;     float* Ms = Za;
;     const int r16 = lane & 15, g4 = lane >> 4;
;     if (wave == 0) {
.LBB0_321:
	v_add_f32_e32 v28, v48, v49
	v_pk_mul_f32 v[24:25], v[30:31], v[28:29] op_sel_hi:[1,0]
	v_pk_mul_f32 v[18:19], v[18:19], v[28:29] op_sel_hi:[1,0]
	v_cvt_pk_bf16_f32 v24, v24, v25
	v_cvt_pk_bf16_f32 v25, v18, v19
	v_pk_mul_f32 v[18:19], v[22:23], v[28:29] op_sel_hi:[1,0]
	s_ashr_i32 s55, s54, 31
	v_cvt_pk_bf16_f32 v26, v18, v19
	v_pk_mul_f32 v[18:19], v[20:21], v[28:29] op_sel_hi:[1,0]
	s_lshl_b64 s[58:59], s[54:55], 13
	v_cvt_pk_bf16_f32 v27, v18, v19
	v_lshl_add_u64 v[18:19], v[138:139], 0, s[58:59]
	global_store_dwordx4 v[18:19], v[24:27], off
	s_waitcnt lgkmcnt(0)
	s_barrier
	ds_read_b128 v[18:21], v188 offset:9472
	ds_read_b128 v[22:25], v187 offset:256
	ds_read_b128 v[26:29], v187 offset:320
	ds_read_b128 v[30:33], v188 offset:9536
	ds_read_b128 v[38:41], v188 offset:11776
	ds_read_b128 v[46:49], v188 offset:11840
	ds_read_b128 v[54:57], v188 offset:18688
	ds_read_b128 v[58:61], v188 offset:18752
	ds_read_b128 v[66:69], v187 offset:27904
	ds_read_b128 v[70:73], v187 offset:27968
	s_waitcnt lgkmcnt(8)
	v_mfma_f32_16x16x32_bf16 v[34:37], v[18:21], v[22:25], 0
	s_waitcnt lgkmcnt(1)
	v_mfma_f32_16x16x32_bf16 v[18:21], v[18:21], v[66:69], 0
	v_mfma_f32_16x16x32_bf16 v[34:37], v[30:33], v[26:29], v[34:37]
	v_mfma_f32_16x16x32_bf16 v[62:65], v[54:57], v[22:25], 0
	s_waitcnt lgkmcnt(0)
	v_mfma_f32_16x16x32_bf16 v[18:21], v[30:33], v[70:73], v[18:21]
	s_nop 4
	v_cndmask_b32_e64 v34, 0, v34, s[14:15]
	v_cndmask_b32_e64 v35, 0, v35, s[18:19]
	v_cndmask_b32_e64 v36, 0, v36, s[20:21]
	v_mfma_f32_16x16x32_bf16 v[30:33], v[54:57], v[66:69], 0
	ds_read_b128 v[54:57], v188 offset:20992
	ds_read_b128 v[74:77], v188 offset:21056
	v_cndmask_b32_e64 v37, 0, v37, s[24:25]
	ds_write_b128 v229, v[34:37]
	v_mfma_f32_16x16x32_bf16 v[50:53], v[38:41], v[22:25], 0
	s_waitcnt lgkmcnt(2)
	v_mfma_f32_16x16x32_bf16 v[22:25], v[54:57], v[22:25], 0
	v_mfma_f32_16x16x32_bf16 v[50:53], v[46:49], v[26:29], v[50:53]
	v_mfma_f32_16x16x32_bf16 v[62:65], v[58:61], v[26:29], v[62:65]
	v_mfma_f32_16x16x32_bf16 v[30:33], v[58:61], v[70:73], v[30:33]
	v_cndmask_b32_e64 v59, v18, 0, s[16:17]
	v_cndmask_b32_e64 v61, 0, v19, s[14:15]
	s_nop 4
	v_cndmask_b32_e64 v58, 0, v62, s[14:15]
	s_waitcnt lgkmcnt(1)
	v_mfma_f32_16x16x32_bf16 v[22:25], v[74:77], v[26:29], v[22:25]
	v_mfma_f32_16x16x32_bf16 v[26:29], v[38:41], v[66:69], 0
	v_cndmask_b32_e64 v38, v20, 0, s[22:23]
	v_cndmask_b32_e64 v40, v21, 0, s[26:27]
	v_cndmask_b32_e64 v60, v30, 0, s[16:17]
	v_mfma_f32_16x16x32_bf16 v[18:21], v[54:57], v[66:69], 0
	v_cndmask_b32_e64 v30, 0, v63, s[18:19]
	v_cndmask_b32_e64 v62, 0, v31, s[14:15]
	v_cndmask_b32_e64 v31, 0, v64, s[20:21]
	v_mfma_f32_16x16x32_bf16 v[26:29], v[46:49], v[70:73], v[26:29]
	v_cndmask_b32_e64 v39, 0, v65, s[24:25]
	v_cvt_pk_bf16_f32 v30, v58, v30
	v_cvt_pk_bf16_f32 v31, v31, v39
	v_mfma_f32_16x16x32_bf16 v[18:21], v[74:77], v[70:73], v[18:21]
	v_cndmask_b32_e64 v32, v32, 0, s[22:23]
	v_cndmask_b32_e64 v33, v33, 0, s[26:27]
	ds_write_b64 v230, v[30:31]
	v_cvt_pk_bf16_f32 v30, v59, v61
	v_cvt_pk_bf16_f32 v31, v38, v40
	ds_write_b64 v231, v[30:31]
	v_cvt_pk_bf16_f32 v30, v60, v62
	v_cvt_pk_bf16_f32 v31, v32, v33
	v_cndmask_b32_e64 v22, 0, v22, s[28:29]
	v_cndmask_b32_e64 v34, v18, 0, s[30:31]
	v_cndmask_b32_e64 v18, 0, v23, s[34:35]
	v_cndmask_b32_e64 v23, 0, v27, s[28:29]
	v_cndmask_b32_e64 v27, 0, v19, s[28:29]
	v_cndmask_b32_e64 v19, 0, v24, s[36:37]
	v_cndmask_b32_e64 v25, 0, v25, s[40:41]
	ds_write_b64 v232, v[30:31]
	v_cndmask_b32_e64 v30, 0, v50, s[28:29]
	v_cndmask_b32_e64 v26, v26, 0, s[30:31]
	v_cndmask_b32_e64 v31, 0, v51, s[34:35]
	v_cndmask_b32_e64 v32, 0, v52, s[36:37]
	v_cndmask_b32_e64 v24, v28, 0, s[38:39]
	v_cndmask_b32_e64 v33, 0, v53, s[40:41]
	v_cndmask_b32_e64 v28, v29, 0, s[42:43]
	v_cvt_pk_bf16_f32 v18, v22, v18
	v_cvt_pk_bf16_f32 v19, v19, v25
	v_cndmask_b32_e64 v20, v20, 0, s[38:39]
	v_cndmask_b32_e64 v21, v21, 0, s[42:43]
	ds_write_b128 v235, v[30:33]
	ds_write_b64 v236, v[18:19]
	v_cvt_pk_bf16_f32 v18, v26, v23
	v_cvt_pk_bf16_f32 v19, v24, v28
	ds_write_b64 v237, v[18:19]
	v_cvt_pk_bf16_f32 v18, v34, v27
	v_cvt_pk_bf16_f32 v19, v20, v21
	ds_write_b64 v238, v[18:19]
	s_waitcnt lgkmcnt(0)
	s_barrier
	s_and_saveexec_b64 s[58:59], s[4:5]
	s_cbranch_execz .LBB0_323
; __device__ void rwkv_prep_item(const Params& p, char* lds_, int item, PrepRaw& raw, int next_item) {
;     ...
;     if (wave == 0) {
;       const float* Lk = Tf + (16 * g4) * 68 + 16 * g4;
;       float xv[16];
; #pragma unroll
;       for (int i = 0; i < 16; ++i) {
;         float sacc = (i == r16) ? 1.f : 0.f;
; #pragma unroll
;         for (int q = 0; q < (i + 3) / 4; ++q) {
;           const f32x4 Lv = *(const f32x4*)(Lk + i * 68 + 4 * q);
; #pragma unroll
;           for (int e = 0; e < 4; ++e)
;             if (4 * q + e < i) sacc += Lv[e] * xv[4 * q + e];
;         }
;         xv[i] = sacc;
;       }
;       float* Dk = Tf + (16 * g4) * 68 + 16 * g4 + r16;
; #pragma unroll
;       for (int i = 0; i < 16; ++i) Dk[i * 68] = xv[i];
;     }
	ds_read_b128 v[18:21], v189 offset:272
	s_waitcnt lgkmcnt(0)
	ds_read_b128 v[20:23], v189 offset:544
	s_waitcnt lgkmcnt(0)
	ds_read_b128 v[22:25], v189 offset:816
	ds_read_b128 v[26:29], v189 offset:1088
	v_fma_f32 v30, v190, v18, v191
	v_fma_f32 v31, v190, v20, v253
	v_fmac_f32_e32 v31, v21, v30
	ds_read_b128 v[18:21], v189 offset:1360
	s_waitcnt lgkmcnt(2)
	v_fma_f32 v32, v190, v22, v254
	v_fmac_f32_e32 v32, v23, v30
	v_fmac_f32_e32 v32, v24, v31
	s_waitcnt lgkmcnt(1)
	v_fma_f32 v33, v190, v26, v255
	ds_read_b128 v[22:25], v189 offset:1376
	v_fmac_f32_e32 v33, v30, v27
	s_waitcnt lgkmcnt(1)
	v_fma_f32 v34, v190, v18, v241
	s_waitcnt lgkmcnt(0)
	ds_read_b128 v[24:27], v189 offset:1632
	v_fmac_f32_e32 v34, v30, v19
	v_fmac_f32_e32 v33, v28, v31
	v_fmac_f32_e32 v34, v20, v31
	v_fmac_f32_e32 v33, v29, v32
	v_fmac_f32_e32 v34, v21, v32
	ds_read_b128 v[18:21], v189 offset:1648
	v_fmac_f32_e32 v34, v22, v33
	s_waitcnt lgkmcnt(0)
	ds_read_b128 v[20:23], v189 offset:1904
	v_cmp_eq_u32_e32 vcc, 6, v174
	s_nop 1
	v_cndmask_b32_e64 v35, 0, 1.0, vcc
	v_fma_f32 v35, v190, v24, v35
	v_fmac_f32_e32 v35, v30, v25
	v_fmac_f32_e32 v35, v31, v26
	v_fmac_f32_e32 v35, v27, v32
	ds_read_b128 v[24:27], v189 offset:1920
	v_fmac_f32_e32 v35, v18, v33
	s_waitcnt lgkmcnt(1)
	v_cmp_eq_u32_e32 vcc, 7, v174
	s_nop 1
	v_cndmask_b32_e64 v36, 0, 1.0, vcc
	v_fma_f32 v36, v190, v20, v36
	v_fmac_f32_e32 v35, v19, v34
	v_fmac_f32_e32 v36, v30, v21
	ds_read_b128 v[18:21], v189 offset:2176
	v_fmac_f32_e32 v36, v31, v22
	v_fmac_f32_e32 v36, v32, v23
	s_waitcnt lgkmcnt(1)
	v_fmac_f32_e32 v36, v33, v24
	v_fmac_f32_e32 v36, v25, v34
	ds_read_b128 v[22:25], v189 offset:2192
	s_waitcnt lgkmcnt(1)
	v_cmp_eq_u32_e32 vcc, 8, v174
	s_nop 1
	v_cndmask_b32_e64 v37, 0, 1.0, vcc
	v_fma_f32 v37, v190, v18, v37
	v_fmac_f32_e32 v37, v30, v19
	v_fmac_f32_e32 v37, v31, v20
	v_fmac_f32_e32 v37, v32, v21
	ds_read_b128 v[18:21], v189 offset:2448
	s_waitcnt lgkmcnt(1)
	v_fmac_f32_e32 v37, v33, v22
	v_fmac_f32_e32 v37, v34, v23
	v_fmac_f32_e32 v36, v26, v35
	v_fmac_f32_e32 v37, v24, v35
	v_fmac_f32_e32 v37, v25, v36
	ds_read_b128 v[22:25], v189 offset:2464
	s_waitcnt lgkmcnt(1)
	v_cmp_eq_u32_e32 vcc, 9, v174
	s_nop 1
	v_cndmask_b32_e64 v38, 0, 1.0, vcc
	v_fma_f32 v38, v190, v18, v38
	v_fmac_f32_e32 v38, v30, v19
	v_fmac_f32_e32 v38, v31, v20
	v_fmac_f32_e32 v38, v32, v21
	s_waitcnt lgkmcnt(0)
	v_fmac_f32_e32 v38, v33, v22
	ds_read_b128 v[18:21], v189 offset:2480
	ds_read_b128 v[26:29], v189 offset:2720
	v_fmac_f32_e32 v38, v34, v23
	v_fmac_f32_e32 v38, v24, v35
	v_fmac_f32_e32 v38, v25, v36
	s_waitcnt lgkmcnt(1)
	v_fmac_f32_e32 v38, v18, v37
	ds_read_b128 v[18:21], v189 offset:2736
	ds_read_b128 v[22:25], v189 offset:2752
	s_waitcnt lgkmcnt(2)
	v_cmp_eq_u32_e32 vcc, 10, v174
	s_nop 1
	v_cndmask_b32_e64 v39, 0, 1.0, vcc
	v_fma_f32 v39, v190, v26, v39
	v_fmac_f32_e32 v39, v30, v27
	v_fmac_f32_e32 v39, v31, v28
	v_fmac_f32_e32 v39, v32, v29
	s_waitcnt lgkmcnt(0)
	ds_read_b128 v[24:27], v189 offset:2992
	v_fmac_f32_e32 v39, v33, v18
	v_fmac_f32_e32 v39, v34, v19
	v_fmac_f32_e32 v39, v35, v20
	v_fmac_f32_e32 v39, v21, v36
	ds_read_b128 v[18:21], v189 offset:3008
	s_waitcnt lgkmcnt(1)
	v_cmp_eq_u32_e32 vcc, 11, v174
	s_nop 1
	v_cndmask_b32_e64 v40, 0, 1.0, vcc
	v_fma_f32 v40, v190, v24, v40
	v_fmac_f32_e32 v40, v30, v25
	v_fmac_f32_e32 v39, v22, v37
	v_fmac_f32_e32 v40, v31, v26
	v_fmac_f32_e32 v39, v23, v38
	v_fmac_f32_e32 v40, v32, v27
	ds_read_b128 v[22:25], v189 offset:3024
	ds_read_b128 v[26:29], v189 offset:3264
	s_waitcnt lgkmcnt(2)
	v_fmac_f32_e32 v40, v33, v18
	v_fmac_f32_e32 v40, v34, v19
	v_fmac_f32_e32 v40, v35, v20
	v_fmac_f32_e32 v40, v36, v21
	ds_read_b128 v[18:21], v189 offset:3280
	s_waitcnt lgkmcnt(1)
	v_cmp_eq_u32_e32 vcc, 12, v174
	s_nop 1
	v_cndmask_b32_e64 v41, 0, 1.0, vcc
	v_fma_f32 v41, v190, v26, v41
	v_fmac_f32_e32 v40, v37, v22
	v_fmac_f32_e32 v41, v30, v27
	v_fmac_f32_e32 v40, v23, v38
	v_fmac_f32_e32 v41, v31, v28
	v_fmac_f32_e32 v40, v24, v39
	v_fmac_f32_e32 v41, v32, v29
	ds_read_b128 v[22:25], v189 offset:3296
	s_waitcnt lgkmcnt(1)
	v_fmac_f32_e32 v41, v33, v18
	v_fmac_f32_e32 v41, v34, v19
	v_fmac_f32_e32 v41, v35, v20
	v_fmac_f32_e32 v41, v36, v21
	ds_read_b128 v[18:21], v189 offset:3536
	s_waitcnt lgkmcnt(1)
	v_fmac_f32_e32 v41, v37, v22
	v_fmac_f32_e32 v41, v38, v23
	v_fmac_f32_e32 v41, v24, v39
	v_fmac_f32_e32 v41, v25, v40
	ds_read_b128 v[22:25], v189 offset:3552
	s_waitcnt lgkmcnt(1)
	v_cmp_eq_u32_e32 vcc, 13, v174
	s_nop 1
	v_cndmask_b32_e64 v28, 0, 1.0, vcc
	v_fma_f32 v28, v190, v18, v28
	v_fmac_f32_e32 v28, v30, v19
	v_fmac_f32_e32 v28, v31, v20
	v_fmac_f32_e32 v28, v32, v21
	s_waitcnt lgkmcnt(0)
	v_fmac_f32_e32 v28, v33, v22
	ds_read_b128 v[18:21], v189 offset:3568
	v_fmac_f32_e32 v28, v34, v23
	v_fmac_f32_e32 v28, v35, v24
	v_fmac_f32_e32 v28, v36, v25
	ds_read_b128 v[22:25], v189 offset:3584
	s_waitcnt lgkmcnt(0)
	ds_read_b128 v[24:27], v189 offset:3808
	v_fmac_f32_e32 v28, v37, v18
	v_fmac_f32_e32 v28, v38, v19
	v_fmac_f32_e32 v28, v20, v39
	v_fmac_f32_e32 v28, v21, v40
	ds_read_b128 v[18:21], v189 offset:3824
	s_waitcnt lgkmcnt(1)
	v_fma_f32 v29, v190, v24, v204
	v_fmac_f32_e32 v29, v30, v25
	v_fmac_f32_e32 v29, v31, v26
	v_fmac_f32_e32 v28, v22, v41
	v_fmac_f32_e32 v29, v32, v27
	ds_read_b128 v[22:25], v189 offset:3840
	s_waitcnt lgkmcnt(1)
	v_fmac_f32_e32 v29, v33, v18
	v_fmac_f32_e32 v29, v34, v19
	v_fmac_f32_e32 v29, v35, v20
	v_fmac_f32_e32 v29, v36, v21
	ds_read_b128 v[18:21], v189 offset:3856
	s_waitcnt lgkmcnt(1)
	v_fmac_f32_e32 v29, v37, v22
	v_fmac_f32_e32 v29, v38, v23
	s_waitcnt lgkmcnt(0)
	ds_read_b128 v[20:23], v189 offset:4080
	v_fmac_f32_e32 v29, v39, v24
	v_fmac_f32_e32 v29, v25, v40
	ds_read_b128 v[24:27], v189 offset:4096
	v_fmac_f32_e32 v29, v18, v41
	s_waitcnt lgkmcnt(1)
	v_fma_f32 v46, v190, v20, v205
	v_fmac_f32_e32 v46, v30, v21
	v_fmac_f32_e32 v46, v31, v22
	v_fmac_f32_e32 v29, v19, v28
	v_fmac_f32_e32 v46, v32, v23
	ds_read_b128 v[18:21], v189 offset:4112
	s_waitcnt lgkmcnt(1)
	v_fmac_f32_e32 v46, v33, v24
	v_fmac_f32_e32 v46, v34, v25
	v_fmac_f32_e32 v46, v35, v26
	v_fmac_f32_e32 v46, v36, v27
	ds_read_b128 v[22:25], v189 offset:4128
	s_waitcnt lgkmcnt(1)
	v_fmac_f32_e32 v46, v37, v18
	v_fmac_f32_e32 v46, v38, v19
	v_fmac_f32_e32 v46, v39, v20
	v_fmac_f32_e32 v46, v40, v21
	v_add_u32_e32 v18, 0x400, v206
	s_waitcnt lgkmcnt(0)
	v_fmac_f32_e32 v46, v41, v22
	ds_write2_b32 v206, v190, v30 offset1:68
	ds_write2_b32 v206, v31, v32 offset0:136 offset1:204
	ds_write2_b32 v18, v33, v34 offset0:16 offset1:84
	ds_write2_b32 v18, v35, v36 offset0:152 offset1:220
	v_add_u32_e32 v18, 0x800, v206
	v_fmac_f32_e32 v46, v23, v28
	ds_write2_b32 v18, v37, v38 offset0:32 offset1:100
	ds_write2_b32 v18, v39, v40 offset0:168 offset1:236
	v_add_u32_e32 v18, 0xc00, v206
	v_fmac_f32_e32 v46, v24, v29
	ds_write2_b32 v18, v41, v28 offset0:48 offset1:116
	ds_write2_b32 v18, v29, v46 offset0:184 offset1:252

; __device__ void phase_scan(const Params& p, int bid, int nb) {
;   const int tid = threadIdx.x, lane = tid & 63, wave = tid >> 6;
;   const int r = lane & 15, g = lane >> 4;
;   const int nsb = nb < 32 ? nb : 32;
;   if (bid >= nsb) return;
;   for (int chain = bid * 8 + wave; chain < 256; chain += nsb * 8) {
;     const int bh = chain >> 2, v0 = (chain & 3) * 16;
.LBB0_329:
	v_lshrrev_b32_e32 v158, 6, v223
	v_mov_b32_e32 v241, v242
	v_and_b32_e32 v242, 31, v223
